# stack22: stack20 + sample-NSA top-k count rewrite + sample-NSA query loads issued together with the key-row loads (one wait instead of four)
# speedup vs baseline: 1.0122x; 1.0029x over previous
.LBB0_1408:
	s_ashr_i32 s0, s2, 2
	s_add_i32 s6, s0, 0x4000
	v_writelane_b32 v247, s0, 56
	s_mov_b32 s0, s6
	s_and_b32 s3, s2, 3
	v_writelane_b32 v247, s0, 16
	s_mul_i32 s5, s6, 0x3e00
	s_mul_hi_i32 s4, s6, 0x3e00
	v_writelane_b32 v247, s1, 17
	s_add_u32 s0, s80, s5
	s_addc_u32 s1, s81, s4
	v_mov_b32_e32 v117, v83
	v_lshl_add_u64 v[2:3], s[0:1], 0, v[116:117]
	s_lshl_b32 s34, s3, 9
	v_lshl_add_u64 v[2:3], v[2:3], 0, s[34:35]
	s_mov_b64 s[0:1], 0x5329c00
	v_lshl_add_u64 v[4:5], v[2:3], 0, s[0:1]
	s_mov_b32 s0, 0x5329000
	v_add_co_u32_e32 v2, vcc, s0, v2
	v_writelane_b32 v247, s3, 50
	s_nop 0
	v_addc_co_u32_e32 v3, vcc, 0, v3, vcc
	global_load_dwordx2 v[42:43], v[2:3], off offset:3072
	global_load_dwordx2 v[44:45], v[4:5], off offset:128
	global_load_dwordx2 v[46:47], v[4:5], off offset:256
	global_load_dwordx2 v[48:49], v[4:5], off offset:384
	s_mov_b32 s0, s2
	s_ashr_i32 s3, s2, 31
	v_writelane_b32 v247, s0, 58
	v_mov_b32_e32 v33, v83
	v_mov_b32_e32 v35, v83
	v_writelane_b32 v247, s1, 59
	s_lshl_b64 s[0:1], s[2:3], 16
	s_mov_b32 s2, 0xe000
	v_mov_b32_e32 v37, v83
	v_lshl_add_u64 v[2:3], v[104:105], 0, s[0:1]
	v_lshl_add_u64 v[4:5], v[2:3], 0, v[102:103]
	global_load_dwordx2 v[14:15], v[4:5], off
	v_lshl_add_u64 v[4:5], v[2:3], 0, v[100:101]
	global_load_dwordx2 v[18:19], v[4:5], off
	v_lshl_add_u64 v[4:5], v[2:3], 0, v[98:99]
	global_load_dwordx2 v[22:23], v[4:5], off
	v_lshl_add_u64 v[4:5], v[2:3], 0, v[96:97]
	global_load_dwordx2 v[24:25], v[4:5], off
	v_lshl_add_u64 v[4:5], v[2:3], 0, v[94:95]
	global_load_dwordx2 v[26:27], v[4:5], off
	v_lshl_add_u64 v[4:5], v[2:3], 0, v[92:93]
	global_load_dwordx2 v[28:29], v[4:5], off
	v_lshl_add_u64 v[4:5], v[2:3], 0, v[90:91]
	global_load_dwordx2 v[30:31], v[4:5], off
	v_lshl_add_u64 v[4:5], v[2:3], 0, v[88:89]
	global_load_dwordx2 v[6:7], v[4:5], off
	s_waitcnt vmcnt(0)
	v_lshlrev_b32_e32 v193, 16, v42
	v_and_b32_e32 v196, 0xffff0000, v42
	v_lshlrev_b32_e32 v194, 16, v43
	v_and_b32_e32 v195, 0xffff0000, v43
	v_lshlrev_b32_e32 v189, 16, v44
	v_and_b32_e32 v192, 0xffff0000, v44
	v_lshlrev_b32_e32 v190, 16, v45
	v_and_b32_e32 v191, 0xffff0000, v45
	v_lshlrev_b32_e32 v185, 16, v46
	v_and_b32_e32 v188, 0xffff0000, v46
	v_lshlrev_b32_e32 v186, 16, v47
	v_and_b32_e32 v187, 0xffff0000, v47
	v_lshlrev_b32_e32 v117, 16, v48
	v_and_b32_e32 v184, 0xffff0000, v48
	v_lshlrev_b32_e32 v121, 16, v49
	v_and_b32_e32 v183, 0xffff0000, v49
	v_lshlrev_b32_e32 v38, 16, v6
	v_and_b32_e32 v39, 0xffff0000, v6
	v_lshlrev_b32_e32 v40, 16, v7
	v_and_b32_e32 v41, 0xffff0000, v7
	v_lshl_add_u64 v[6:7], v[2:3], 0, v[106:107]
	global_load_dwordx2 v[20:21], v[6:7], off
	v_add_co_u32_e32 v6, vcc, s93, v4
	v_lshl_add_u64 v[2:3], v[2:3], 0, v[108:109]
	s_nop 0
	v_addc_co_u32_e32 v7, vcc, 0, v5, vcc
	global_load_dwordx2 v[16:17], v[6:7], off offset:-4096
	global_load_dwordx2 v[12:13], v[6:7], off
	v_add_co_u32_e32 v6, vcc, s95, v4
	v_mul_f32_e32 v32, v39, v196
	s_nop 0
	v_addc_co_u32_e32 v7, vcc, 0, v5, vcc
	v_add_co_u32_e32 v4, vcc, s2, v4
	global_load_dwordx2 v[10:11], v[6:7], off offset:-4096
	global_load_dwordx2 v[8:9], v[6:7], off
	v_addc_co_u32_e32 v5, vcc, 0, v5, vcc
	v_add_co_u32_e32 v2, vcc, s97, v2
	global_load_dwordx2 v[6:7], v[4:5], off offset:-4096
	s_nop 0
	global_load_dwordx2 v[4:5], v[4:5], off
	v_addc_co_u32_e32 v3, vcc, 0, v3, vcc
	global_load_dwordx2 v[2:3], v[2:3], off
	v_mul_f32_e32 v34, v39, v192
	v_mul_f32_e32 v36, v39, v188
	v_mul_f32_e32 v39, v39, v184
	v_fmac_f32_e32 v32, v38, v193
	v_fmac_f32_e32 v34, v38, v189
	v_fmac_f32_e32 v36, v38, v185
	v_fmac_f32_e32 v39, v38, v117
	v_fmac_f32_e32 v32, v40, v194
	v_fmac_f32_e32 v34, v40, v190
	v_fmac_f32_e32 v36, v40, v186
	v_fmac_f32_e32 v39, v40, v121
	v_fmac_f32_e32 v32, v41, v195
	v_fmac_f32_e32 v34, v41, v191
	v_fmac_f32_e32 v36, v41, v187
	v_fmac_f32_e32 v39, v41, v183
	v_add_f32_dpp v32, v32, v32 quad_perm:[1,0,3,2] row_mask:0xf bank_mask:0xf bound_ctrl:1
	v_add_f32_dpp v34, v34, v34 quad_perm:[1,0,3,2] row_mask:0xf bank_mask:0xf bound_ctrl:1
	v_add_f32_dpp v36, v36, v36 quad_perm:[1,0,3,2] row_mask:0xf bank_mask:0xf bound_ctrl:1
	v_add_f32_dpp v38, v39, v39 quad_perm:[1,0,3,2] row_mask:0xf bank_mask:0xf bound_ctrl:1
	v_add_f32_dpp v32, v32, v32 quad_perm:[2,3,0,1] row_mask:0xf bank_mask:0xf bound_ctrl:1
	v_add_f32_dpp v34, v34, v34 quad_perm:[2,3,0,1] row_mask:0xf bank_mask:0xf bound_ctrl:1
	v_add_f32_dpp v36, v36, v36 quad_perm:[2,3,0,1] row_mask:0xf bank_mask:0xf bound_ctrl:1
	v_add_f32_dpp v38, v38, v38 quad_perm:[2,3,0,1] row_mask:0xf bank_mask:0xf bound_ctrl:1
	v_add_f32_dpp v32, v32, v32 row_half_mirror row_mask:0xf bank_mask:0xf bound_ctrl:1
	v_add_f32_dpp v34, v34, v34 row_half_mirror row_mask:0xf bank_mask:0xf bound_ctrl:1
	v_add_f32_dpp v36, v36, v36 row_half_mirror row_mask:0xf bank_mask:0xf bound_ctrl:1
	v_add_f32_dpp v38, v38, v38 row_half_mirror row_mask:0xf bank_mask:0xf bound_ctrl:1
	v_mov_b32_e32 v39, v83
	v_mov_b32_dpp v33, v32 row_mirror row_mask:0xf bank_mask:0xf
	v_mov_b32_dpp v35, v34 row_mirror row_mask:0xf bank_mask:0xf
	v_mov_b32_dpp v37, v36 row_mirror row_mask:0xf bank_mask:0xf
	v_mov_b32_dpp v39, v38 row_mirror row_mask:0xf bank_mask:0xf
	s_and_saveexec_b64 s[2:3], s[44:45]
	s_cbranch_execz .LBB0_1410
	v_add_f32_e32 v32, v32, v33
	v_add_f32_e32 v38, v38, v39
	v_add_f32_e32 v36, v36, v37
	v_add_f32_e32 v34, v34, v35
	ds_write_b32 v141, v32
	ds_write_b32 v141, v34 offset:4224
	ds_write_b32 v141, v36 offset:8448
	ds_write_b32 v141, v38 offset:12672

.LBB0_1469:
	s_waitcnt vmcnt(0)
	v_lshlrev_b32_e64 v20, v9, 1
	v_or_b32_e32 v20, v20, v3
	v_mov_b32_e32 v21, 0
	v_cmp_ge_u32_e64 s[0:1], v19, v20
	v_cmp_ge_u32_e64 s[98:99], v17, v20
	v_cmp_ge_u32_e64 s[100:101], v18, v20
	v_cmp_ge_u32_e32 vcc, v15, v20
	v_addc_co_u32_e64 v21, s[0:1], 0, v21, s[0:1]
	v_addc_co_u32_e64 v21, s[98:99], 0, v21, s[98:99]
	v_addc_co_u32_e64 v21, s[100:101], 0, v21, s[100:101]
	v_addc_co_u32_e32 v21, vcc, 0, v21, vcc
	v_cmp_ge_u32_e64 s[0:1], v14, v20
	v_cmp_ge_u32_e64 s[98:99], v13, v20
	v_cmp_ge_u32_e64 s[100:101], v12, v20
	v_cmp_ge_u32_e32 vcc, v11, v20
	v_addc_co_u32_e64 v21, s[0:1], 0, v21, s[0:1]
	v_addc_co_u32_e64 v21, s[98:99], 0, v21, s[98:99]
	v_addc_co_u32_e64 v21, s[100:101], 0, v21, s[100:101]
	v_addc_co_u32_e32 v21, vcc, 0, v21, vcc
	v_cmp_ge_u32_e64 s[0:1], v10, v20
	v_cmp_ge_u32_e64 s[98:99], v8, v20
	v_cmp_ge_u32_e64 s[100:101], v7, v20
	v_cmp_ge_u32_e32 vcc, v6, v20
	v_addc_co_u32_e64 v21, s[0:1], 0, v21, s[0:1]
	v_addc_co_u32_e64 v21, s[98:99], 0, v21, s[98:99]
	v_addc_co_u32_e64 v21, s[100:101], 0, v21, s[100:101]
	v_addc_co_u32_e32 v21, vcc, 0, v21, vcc
	v_cmp_ge_u32_e64 s[0:1], v5, v20
	v_cmp_ge_u32_e64 s[98:99], v4, v20
	v_cmp_ge_u32_e64 s[100:101], v2, v20
	v_cmp_ge_u32_e32 vcc, v16, v20
	v_addc_co_u32_e64 v21, s[0:1], 0, v21, s[0:1]
	v_addc_co_u32_e64 v21, s[98:99], 0, v21, s[98:99]
	v_addc_co_u32_e64 v21, s[100:101], 0, v21, s[100:101]
	v_addc_co_u32_e32 v21, vcc, 0, v21, vcc
	s_nop 1
	v_add_u32_dpp v21, v21, v21 quad_perm:[1,0,3,2] row_mask:0xf bank_mask:0xf bound_ctrl:1
	s_nop 1
	v_add_u32_dpp v21, v21, v21 quad_perm:[2,3,0,1] row_mask:0xf bank_mask:0xf bound_ctrl:1
	s_nop 1
	v_add_u32_dpp v21, v21, v21 row_half_mirror row_mask:0xf bank_mask:0xf bound_ctrl:1
	v_cmp_eq_u32_e64 s[0:1], 13, v21
	v_cmp_gt_i32_e32 vcc, 13, v21
	s_or_b64 s[0:1], s[2:3], s[0:1]
	s_or_b64 vcc, s[2:3], vcc
	s_xor_b64 s[2:3], s[0:1], -1
	v_cndmask_b32_e32 v3, v20, v3, vcc
	v_cndmask_b32_e64 v20, 0, 1, s[2:3]
	v_cmp_ne_u32_e32 vcc, 0, v20
	s_cmp_eq_u64 vcc, 0
	s_cselect_b64 s[2:3], -1, 0
	v_subrev_co_u32_e32 v9, vcc, 1, v9
	s_or_b64 s[2:3], s[2:3], vcc
	s_andn2_b64 vcc, exec, s[2:3]
	s_mov_b64 s[2:3], s[0:1]
	s_cbranch_vccnz .LBB0_1469
	v_cmp_ne_u32_e32 vcc, 0, v3
	s_and_saveexec_b64 s[0:1], vcc
	s_xor_b64 s[46:47], exec, s[0:1]
	s_cbranch_execz .LBB0_1472
	v_cmp_gt_u32_e64 s[14:15], v19, v3
	v_cmp_gt_u32_e64 s[12:13], v17, v3
	v_cmp_eq_u32_e64 s[2:3], v17, v3
	v_cndmask_b32_e64 v17, 0, 1, s[14:15]
	v_cmp_eq_u32_e64 s[40:41], v19, v3
	v_cmp_gt_u32_e64 s[20:21], v18, v3
	v_addc_co_u32_e64 v17, vcc, 0, v17, s[12:13]
	v_cndmask_b32_e64 v19, 0, 1, s[40:41]
	v_cndmask_b32_e64 v21, 0, 1, s[20:21]
	v_cmp_eq_u32_e64 s[38:39], v18, v3
	v_cmp_gt_u32_e64 s[16:17], v15, v3
	v_cmp_gt_u32_e64 s[10:11], v14, v3
	v_addc_co_u32_e64 v20, vcc, 0, v19, s[2:3]
	v_cndmask_b32_e64 v18, 0, 1, s[38:39]
	v_addc_co_u32_e64 v17, vcc, v17, v21, s[16:17]
	v_cmp_eq_u32_e64 s[8:9], v15, v3
	v_cndmask_b32_e64 v21, 0, 1, s[10:11]
	v_cmp_eq_u32_e64 s[22:23], v14, v3
	v_cmp_gt_u32_e64 s[86:87], v13, v3
	v_cmp_gt_u32_e64 s[36:37], v12, v3
	v_addc_co_u32_e64 v20, vcc, v20, v18, s[8:9]
	v_cndmask_b32_e64 v14, 0, 1, s[22:23]
	v_addc_co_u32_e64 v17, s[0:1], v17, v21, s[86:87]
	v_cmp_eq_u32_e64 s[18:19], v13, v3
	v_cndmask_b32_e64 v21, 0, 1, s[36:37]
	v_cmp_gt_u32_e64 s[4:5], v11, v3
	v_addc_co_u32_e64 v20, s[0:1], v20, v14, s[18:19]
	v_cmp_eq_u32_e64 s[24:25], v12, v3
	v_addc_co_u32_e64 v17, s[0:1], v17, v21, s[4:5]
	v_cmp_gt_u32_e64 s[70:71], v10, v3
	v_cndmask_b32_e64 v12, 0, 1, s[24:25]
	v_cmp_eq_u32_e64 s[0:1], v11, v3
	v_cndmask_b32_e64 v21, 0, 1, s[70:71]
	s_mov_b64 s[28:29], s[84:85]
	s_mov_b64 s[84:85], s[58:59]
	s_mov_b64 s[58:59], s[66:67]
	v_cmp_eq_u32_e64 s[66:67], v10, v3
	v_cmp_gt_u32_e64 s[74:75], v8, v3
	v_cmp_gt_u32_e64 s[72:73], v7, v3
	v_addc_co_u32_e64 v20, s[6:7], v20, v12, s[0:1]
	v_cndmask_b32_e64 v10, 0, 1, s[66:67]
	v_addc_co_u32_e64 v17, s[6:7], v17, v21, s[74:75]
	s_mov_b32 s53, s52
	s_mov_b32 s52, s64
	v_cmp_eq_u32_e64 s[64:65], v8, v3
	v_cndmask_b32_e64 v21, 0, 1, s[72:73]
	v_cmp_gt_u32_e64 s[82:83], v6, v3
	v_addc_co_u32_e64 v20, s[6:7], v20, v10, s[64:65]
	v_cmp_eq_u32_e64 s[68:69], v7, v3
	v_addc_co_u32_e64 v17, s[6:7], v17, v21, s[82:83]
	v_cmp_gt_u32_e64 s[94:95], v5, v3
	v_cndmask_b32_e64 v7, 0, 1, s[68:69]
	v_cmp_eq_u32_e64 s[6:7], v6, v3
	v_cndmask_b32_e64 v21, 0, 1, s[94:95]
	v_cmp_gt_u32_e64 s[90:91], v4, v3
	v_addc_co_u32_e64 v20, s[76:77], v20, v7, s[6:7]
	v_cmp_eq_u32_e64 s[78:79], v5, v3
	v_addc_co_u32_e64 v17, s[76:77], v17, v21, s[90:91]
	s_nop 0
	v_cndmask_b32_e64 v5, 0, 1, s[78:79]
	v_cmp_eq_u32_e64 s[76:77], v4, v3
	v_cmp_gt_u32_e64 s[88:89], v16, v3
	v_cmp_eq_u32_e64 s[96:97], v2, v3
	v_addc_co_u32_e64 v20, s[80:81], v20, v5, s[76:77]
	v_cmp_gt_u32_e64 s[80:81], v2, v3
	s_mov_b32 s34, s92
	v_cndmask_b32_e64 v2, 0, 1, s[96:97]
	v_cndmask_b32_e64 v21, 0, 1, s[80:81]
	v_addc_co_u32_e64 v17, s[92:93], v17, v21, s[88:89]
	v_cmp_eq_u32_e64 s[92:93], v16, v3
	s_nop 0
	v_add_u32_dpp v16, v17, v17 quad_perm:[1,0,3,2] row_mask:0xf bank_mask:0xf bound_ctrl:1
	v_mov_b32_e32 v17, v83
	v_addc_co_u32_e64 v3, vcc, v20, v2, s[92:93]
	v_and_or_b32 v20, v173, 64, v149
	v_lshlrev_b32_e32 v20, 2, v20
	ds_bpermute_b32 v21, v20, v3
	ds_bpermute_b32 v22, v20, v3 offset:4
	v_readlane_b32 vcc_lo, v247, 20
	v_readlane_b32 vcc_hi, v247, 21
	ds_bpermute_b32 v23, v20, v3 offset:8
	v_add_u32_dpp v16, v16, v16 quad_perm:[2,3,0,1] row_mask:0xf bank_mask:0xf bound_ctrl:1
	s_waitcnt lgkmcnt(2)
	v_cndmask_b32_e64 v21, v21, 0, vcc
	v_readlane_b32 vcc_lo, v246, 30
	v_readlane_b32 vcc_hi, v246, 31
	v_mov_b32_dpp v17, v16 row_half_mirror row_mask:0xf bank_mask:0xf
	v_add_u32_e32 v16, v17, v16
	s_waitcnt lgkmcnt(1)
	v_cndmask_b32_e32 v22, 0, v22, vcc
	v_readlane_b32 vcc_lo, v246, 32
	v_readlane_b32 vcc_hi, v246, 33
	v_cndmask_b32_e64 v9, 0, 1, s[2:3]
	v_sub_u32_e32 v16, 13, v16
	s_waitcnt lgkmcnt(0)
	v_cndmask_b32_e32 v23, 0, v23, vcc
	v_add3_u32 v21, v22, v21, v23
	ds_bpermute_b32 v22, v20, v3 offset:12
	ds_bpermute_b32 v23, v20, v3 offset:16
	v_readlane_b32 vcc_lo, v246, 34
	v_readlane_b32 vcc_hi, v246, 35
	v_cndmask_b32_e64 v9, v9, 0, s[12:13]
	v_cndmask_b32_e64 v19, v19, 0, s[14:15]
	s_waitcnt lgkmcnt(1)
	v_cndmask_b32_e32 v22, 0, v22, vcc
	v_readlane_b32 vcc_lo, v246, 36
	v_readlane_b32 vcc_hi, v246, 37
	v_cndmask_b32_e64 v18, v18, 0, s[20:21]
	v_cndmask_b32_e64 v15, 0, 1, s[8:9]
	s_waitcnt lgkmcnt(0)
	v_cndmask_b32_e32 v23, 0, v23, vcc
	v_add3_u32 v21, v21, v22, v23
	ds_bpermute_b32 v22, v20, v3 offset:20
	v_or_b32_e32 v20, 24, v20
	ds_bpermute_b32 v3, v20, v3
	v_readlane_b32 vcc_lo, v246, 38
	v_readlane_b32 vcc_hi, v246, 39
	v_cndmask_b32_e64 v15, v15, 0, s[16:17]
	v_cndmask_b32_e64 v14, v14, 0, s[10:11]
	s_waitcnt lgkmcnt(1)
	v_cndmask_b32_e32 v22, 0, v22, vcc
	v_readlane_b32 vcc_lo, v247, 10
	v_readlane_b32 vcc_hi, v247, 11
	v_cndmask_b32_e64 v13, 0, 1, s[18:19]
	v_cndmask_b32_e64 v13, v13, 0, s[86:87]
	s_waitcnt lgkmcnt(0)
	v_cndmask_b32_e32 v3, 0, v3, vcc
	v_add3_u32 v3, v21, v22, v3
	v_cmp_lt_i32_e32 vcc, v3, v16
	s_and_b64 s[2:3], s[2:3], vcc
	v_add_u32_e32 v3, v3, v9
	s_or_b64 s[2:3], s[12:13], s[2:3]
	v_cmp_lt_i32_e32 vcc, v3, v16
	v_cndmask_b32_e64 v17, 0, 1, s[2:3]
	s_and_b64 s[2:3], s[40:41], vcc
	v_add_u32_e32 v3, v3, v19
	s_or_b64 s[2:3], s[14:15], s[2:3]
	v_cmp_lt_i32_e32 vcc, v3, v16
	v_cndmask_b32_e64 v9, 0, 2, s[2:3]
	s_and_b64 s[2:3], s[38:39], vcc
	v_add_u32_e32 v3, v3, v18
	s_or_b64 s[2:3], s[20:21], s[2:3]
	v_cmp_lt_i32_e32 vcc, v3, v16
	v_or_b32_e32 v9, v9, v17
	v_cndmask_b32_e64 v17, 0, 4, s[2:3]
	s_and_b64 s[2:3], s[8:9], vcc
	v_add_u32_e32 v3, v3, v15
	s_or_b64 s[2:3], s[16:17], s[2:3]
	v_cmp_lt_i32_e32 vcc, v3, v16
	v_cndmask_b32_e64 v18, 0, 8, s[2:3]
	s_and_b64 s[2:3], s[22:23], vcc
	v_add_u32_e32 v3, v3, v14
	s_or_b64 s[2:3], s[10:11], s[2:3]
	v_cmp_lt_i32_e32 vcc, v3, v16
	v_cndmask_b32_e64 v15, 0, 16, s[2:3]
	s_and_b64 s[2:3], s[18:19], vcc
	v_add_u32_e32 v3, v3, v13
	v_cndmask_b32_e64 v12, v12, 0, s[36:37]
	s_or_b64 s[2:3], s[86:87], s[2:3]
	v_cmp_lt_i32_e32 vcc, v3, v16
	v_add_u32_e32 v3, v3, v12
	v_cndmask_b32_e64 v11, 0, 1, s[0:1]
	v_cndmask_b32_e64 v14, 0, 32, s[2:3]
	s_and_b64 s[2:3], s[24:25], vcc
	v_cmp_lt_i32_e32 vcc, v3, v16
	s_and_b64 s[0:1], s[0:1], vcc
	v_cndmask_b32_e64 v11, v11, 0, s[4:5]
	s_or_b64 vcc, s[4:5], s[0:1]
	v_add_u32_e32 v3, v3, v11
	v_cndmask_b32_e32 v12, 0, v174, vcc
	v_cmp_lt_i32_e32 vcc, v3, v16
	s_and_b64 s[0:1], s[66:67], vcc
	v_cndmask_b32_e64 v10, v10, 0, s[70:71]
	s_or_b64 vcc, s[70:71], s[0:1]
	v_add_u32_e32 v3, v3, v10
	v_cndmask_b32_e64 v8, 0, 1, s[64:65]
	v_cndmask_b32_e32 v11, 0, v175, vcc
	v_cmp_lt_i32_e32 vcc, v3, v16
	s_and_b64 s[0:1], s[64:65], vcc
	v_cndmask_b32_e64 v8, v8, 0, s[74:75]
	s_or_b64 vcc, s[74:75], s[0:1]
	v_add_u32_e32 v3, v3, v8
	v_or3_b32 v9, v9, v17, v18
	s_or_b64 s[2:3], s[36:37], s[2:3]
	v_cndmask_b32_e32 v10, 0, v176, vcc
	v_cmp_lt_i32_e32 vcc, v3, v16
	v_or3_b32 v9, v9, v15, v14
	v_cndmask_b32_e64 v13, 0, 64, s[2:3]
	s_and_b64 s[0:1], s[68:69], vcc
	v_cndmask_b32_e64 v7, v7, 0, s[72:73]
	v_or3_b32 v9, v9, v13, v12
	s_or_b64 vcc, s[72:73], s[0:1]
	v_add_u32_e32 v3, v3, v7
	v_cndmask_b32_e64 v6, 0, 1, s[6:7]
	v_or3_b32 v8, v9, v11, v10
	v_cndmask_b32_e32 v9, 0, v177, vcc
	v_cmp_lt_i32_e32 vcc, v3, v16
	s_and_b64 s[0:1], s[6:7], vcc
	v_cndmask_b32_e64 v6, v6, 0, s[82:83]
	s_or_b64 vcc, s[82:83], s[0:1]
	v_add_u32_e32 v3, v3, v6
	v_cndmask_b32_e32 v7, 0, v178, vcc
	v_cmp_lt_i32_e32 vcc, v3, v16
	s_and_b64 s[0:1], s[78:79], vcc
	v_cndmask_b32_e64 v5, v5, 0, s[94:95]
	s_or_b64 vcc, s[94:95], s[0:1]
	v_add_u32_e32 v3, v3, v5
	v_cndmask_b32_e64 v4, 0, 1, s[76:77]
	v_or3_b32 v6, v8, v9, v7
	v_cndmask_b32_e32 v7, 0, v179, vcc
	v_cmp_lt_i32_e32 vcc, v3, v16
	s_and_b64 s[0:1], s[76:77], vcc
	v_cndmask_b32_e64 v4, v4, 0, s[90:91]
	s_or_b64 vcc, s[90:91], s[0:1]
	v_add_u32_e32 v3, v3, v4
	v_cndmask_b32_e32 v5, 0, v180, vcc
	v_cmp_lt_i32_e32 vcc, v3, v16
	s_and_b64 s[0:1], s[96:97], vcc
	v_cndmask_b32_e64 v2, v2, 0, s[80:81]
	s_or_b64 vcc, s[80:81], s[0:1]
	v_add_u32_e32 v2, v3, v2
	v_or3_b32 v4, v6, v7, v5
	v_cndmask_b32_e32 v5, 0, v181, vcc
	v_cmp_lt_i32_e32 vcc, v2, v16
	s_and_b64 s[0:1], s[92:93], vcc
	v_readlane_b32 s94, v247, 42
	v_readlane_b32 s96, v247, 8
	s_or_b64 vcc, s[88:89], s[0:1]
	v_readlane_b32 s86, v248, 40
	v_readlane_b32 s36, v246, 4
	s_mov_b64 s[66:67], s[58:59]
	s_mov_b64 s[58:59], s[84:85]
	s_mov_b64 s[84:85], s[28:29]
	v_readlane_b32 s28, v246, 10
	v_readlane_b32 s70, v246, 2
	v_readlane_b32 s74, v246, 20
	v_readlane_b32 s68, v246, 14
	v_readlane_b32 s72, v246, 18
	v_readlane_b32 s82, v246, 8
	v_readlane_b32 s78, v246, 24
	v_readlane_b32 s95, v247, 43
	v_readlane_b32 s76, v246, 22
	v_readlane_b32 s90, v246, 12
	v_readlane_b32 s97, v247, 9
	v_readlane_b32 s80, v247, 6
	v_cndmask_b32_e32 v2, 0, v87, vcc
	s_movk_i32 s15, 0x280
	s_movk_i32 s14, 0x260
	s_movk_i32 s13, 0x240
	s_movk_i32 s12, 0x220
	s_movk_i32 s23, 0x360
	s_movk_i32 s22, 0x3a0
	s_movk_i32 s21, 0x2c0
	s_mov_b32 s20, 0xff800000
	s_movk_i32 s19, 0x2e0
	s_movk_i32 s18, 0x300
	s_movk_i32 s17, 0x320
	s_movk_i32 s16, 0x340
	v_readlane_b32 s87, v248, 41
	v_readlane_b32 s37, v246, 5
	v_readlane_b32 s29, v246, 11
	v_readlane_b32 s71, v246, 3
	s_movk_i32 s65, 0x200
	s_mov_b32 s64, s52
	s_mov_b32 s52, s53
	s_movk_i32 s53, 0x1e0
	v_readlane_b32 s75, v246, 21
	v_readlane_b32 s69, v246, 15
	v_readlane_b32 s73, v246, 19
	v_readlane_b32 s83, v246, 9
	v_readlane_b32 s79, v246, 25
	s_mov_b32 s95, 0xc000
	v_readlane_b32 s77, v246, 23
	v_readlane_b32 s91, v246, 13
	s_mov_b32 s97, 0xf000
	v_readlane_b32 s81, v247, 7
	s_mov_b32 s93, 0xa000
	s_mov_b32 s92, s34
	s_movk_i32 s34, 0x2a0
	v_or3_b32 v9, v4, v5, v2
